# in-projection epilogues (even + odd): 8 serialized per-row ssq loads (each wait also drained stores) issued together at epilogue start
# baseline (speedup 1.0000x reference)
; __device__ __forceinline__ unsigned cvt_pk_bf16(float lo, float hi) { unsigned r; asm volatile("v_cvt_pk_bf16_f32 %0, %1, %2" : "=v"(r) : "v"(lo), "v"(hi)); return r; }
; __device__ __forceinline__ float gelu_t(float x) { const float z = 1.5957691216f * (x + 0.044715f * x * x * x); return x * sigm(z); }
; #define EPI_FOR_ROWS() _Pragma("unroll") for (int ai = 0; ai < 2; ++ai) _Pragma("unroll") for (int m = 0; m < 4; ++m)
; __device__ __forceinline__ float row_rstd(const float* ssq, int row, int fq) {
;     const f32x4 q = *(const f32x4*)(ssq + (size_t)row * 16 + 4 * fq); float s = (q[0] + q[1]) + (q[2] + q[3]);
;     s += __shfl_xor(s, 16); s += __shfl_xor(s, 32); return rsqrtf(s * (1.0f / 1024.0f) + EPS);
; }
;     __device__ __forceinline__ void operator()(const f32x4 (&acc)[2][2][4][2], const Unit& u, int wr, int wc, int fr, int fq) const {
;     ...
;         EPI_FOR_ROWS() {
;             const int row = row0 + ai * 128 + m * 16; const float rs = row_rstd(ssq, row, fq);
; #pragma unroll
;             for (int bj = 0; bj < 2; ++bj) { const int col = col0 + bj * 128; f32x4 v0 = acc[ai][bj][m][0] * rs, v1 = acc[ai][bj][m][1] * rs;
;                 if (u.pn >= 2) {
; #pragma unroll
;                     for (int e = 0; e < 4; ++e) { v0[e] = gelu_t(v0[e]); v1[e] = gelu_t(v1[e]); } }
;                 u32x4 w; w.x = cvt_pk_bf16(v0[0], v0[1]); w.y = cvt_pk_bf16(v0[2], v0[3]); w.z = cvt_pk_bf16(v1[0], v1[1]); w.w = cvt_pk_bf16(v1[2], v1[3]);
;                 *(u32x4*)(proj + (size_t)row * 1536 + col) = w; }
.LBB0_236:
	v_lshl_add_u32 v130, s57, 8, v140
	v_ashrrev_i32_e32 v131, 31, v130
	v_lshlrev_b64 v[132:133], 6, v[130:131]
	v_lshl_add_u64 v[132:133], v[128:129], 0, v[132:133]
	global_load_dwordx4 v[154:157], v[132:133], off
	global_load_dwordx4 v[166:169], v[132:133], off offset:1024
	global_load_dwordx4 v[178:181], v[132:133], off offset:2048
	global_load_dwordx4 v[182:185], v[132:133], off offset:3072
	v_mov_b32_e32 v188, 0x2000
	v_mov_b32_e32 v189, 0
	v_lshl_add_u64 v[186:187], v[132:133], 0, v[188:189]
	global_load_dwordx4 v[186:189], v[186:187], off
	v_mov_b32_e32 v192, 0x2400
	v_mov_b32_e32 v193, 0
	v_lshl_add_u64 v[190:191], v[132:133], 0, v[192:193]
	global_load_dwordx4 v[190:193], v[190:191], off
	v_mov_b32_e32 v196, 0x2800
	v_mov_b32_e32 v197, 0
	v_lshl_add_u64 v[194:195], v[132:133], 0, v[196:197]
	global_load_dwordx4 v[194:197], v[194:195], off
	v_mov_b32_e32 v200, 0x2c00
	v_mov_b32_e32 v201, 0
	v_lshl_add_u64 v[198:199], v[132:133], 0, v[200:201]
	global_load_dwordx4 v[198:201], v[198:199], off
	s_waitcnt vmcnt(0)
	v_mov_b32_e32 v132, v154
	v_mov_b32_e32 v133, v155
	v_mov_b32_e32 v134, v156
	v_mov_b32_e32 v135, v157
	v_and_b32_e32 v147, 64, v207
	v_xor_b32_e32 v131, 16, v207
	v_add_u32_e32 v147, 64, v147
	v_cmp_lt_i32_e32 vcc, v131, v147
	s_cmp_gt_i32 s56, 1
	v_readlane_b32 s60, v252, 25
	v_cndmask_b32_e32 v131, v207, v131, vcc
	v_lshlrev_b32_e32 v131, 2, v131
	v_readlane_b32 s62, v252, 27
	v_readlane_b32 s58, v252, 21
	s_cselect_b64 s[4:5], -1, 0
	s_cmp_lt_i32 s56, 2
	v_readlane_b32 s61, v252, 26
	v_readlane_b32 s63, v252, 28
	v_readlane_b32 s59, v252, 22
	v_mov_b32_e32 v148, v133
	v_mov_b32_e32 v149, v134
	v_mov_b32_e32 v133, v135
	v_pk_add_f32 v[132:133], v[148:149], v[132:133]
	v_xor_b32_e32 v134, 32, v207
	v_add_f32_e32 v132, v132, v133
	ds_bpermute_b32 v133, v131, v132
	v_cmp_lt_i32_e32 vcc, v134, v147
	s_waitcnt lgkmcnt(0)
	v_add_f32_e32 v132, v132, v133
	v_cndmask_b32_e32 v134, v207, v134, vcc
	v_lshlrev_b32_e32 v147, 2, v134
	ds_bpermute_b32 v133, v147, v132
	s_waitcnt lgkmcnt(0)
	v_add_f32_e32 v132, v132, v133
	v_fmamk_f32 v132, v132, 0x3a800000, v208
	v_mul_f32_e32 v133, 0x4b800000, v132
	v_cmp_gt_f32_e32 vcc, s44, v132
	s_nop 1
	v_cndmask_b32_e32 v132, v132, v133, vcc
	v_rsq_f32_e32 v132, v132
	s_nop 0
	v_mul_f32_e32 v133, 0x45800000, v132
	v_cndmask_b32_e32 v132, v132, v133, vcc
	v_pk_mul_f32 v[126:127], v[126:127], v[132:133] op_sel_hi:[1,0]
	v_pk_mul_f32 v[124:125], v[124:125], v[132:133] op_sel_hi:[1,0]
	v_pk_mul_f32 v[122:123], v[122:123], v[132:133] op_sel_hi:[1,0]
	v_pk_mul_f32 v[134:135], v[120:121], v[132:133] op_sel_hi:[1,0]
	s_cbranch_scc1 .LBB0_238
	v_mul_f32_e32 v121, 0x3d372713, v134
	v_mul_f32_e32 v121, v134, v121
	v_fma_f32 v121, v134, v121, v134
	v_mul_f32_e32 v121, 0x3fcc422a, v121
	v_mul_f32_e32 v121, 0xbfb8aa3b, v121
	v_exp_f32_e32 v121, v121
	v_mov_b32_e32 v133, v125
	v_mov_b32_e32 v149, v135
	v_mul_f32_e32 v120, 0x3d372713, v124
	v_add_f32_e32 v121, 1.0, v121
	v_rcp_f32_e32 v148, v121
	v_mul_f32_e32 v121, 0x3d372713, v125
	v_mul_f32_e32 v121, v125, v121
	v_fmac_f32_e32 v133, v133, v121
	v_mul_f32_e32 v121, 0x3fcc422a, v133
	v_mul_f32_e32 v133, 0x3d372713, v135
	v_mul_f32_e32 v133, v135, v133
	v_fmac_f32_e32 v149, v149, v133
	v_mul_f32_e32 v133, 0x3fcc422a, v149
	v_mul_f32_e32 v133, 0xbfb8aa3b, v133
	v_exp_f32_e32 v133, v133
	v_mul_f32_e32 v120, v124, v120
	v_fma_f32 v120, v124, v120, v124
	v_mul_f32_e32 v120, 0x3fcc422a, v120
	v_add_f32_e32 v133, 1.0, v133
	v_rcp_f32_e32 v149, v133
	v_mul_f32_e32 v133, 0x3d372713, v126
	v_mul_f32_e32 v133, v126, v133
	v_fma_f32 v133, v126, v133, v126
	v_mul_f32_e32 v133, 0x3fcc422a, v133
	v_mul_f32_e32 v133, 0xbfb8aa3b, v133
	v_exp_f32_e32 v133, v133
	v_mul_f32_e32 v120, 0xbfb8aa3b, v120
	v_mul_f32_e32 v121, 0xbfb8aa3b, v121
	v_exp_f32_e32 v120, v120
	v_add_f32_e32 v133, 1.0, v133
	v_rcp_f32_e32 v150, v133
	v_mul_f32_e32 v133, 0x3d372713, v122
	v_exp_f32_e32 v121, v121
	v_mul_f32_e32 v133, v122, v133
	v_fma_f32 v133, v122, v133, v122
	v_mul_f32_e32 v133, 0x3fcc422a, v133
	v_mul_f32_e32 v133, 0xbfb8aa3b, v133
	v_add_f32_e32 v120, 1.0, v120
	v_add_f32_e32 v121, 1.0, v121
	v_exp_f32_e32 v133, v133
	v_rcp_f32_e32 v120, v120
	v_rcp_f32_e32 v121, v121
	v_pk_mul_f32 v[134:135], v[134:135], v[148:149]
	v_add_f32_e32 v133, 1.0, v133
	v_rcp_f32_e32 v152, v133
	v_mul_f32_e32 v133, 0x3d372713, v127
	v_pk_mul_f32 v[124:125], v[124:125], v[120:121]
	v_mul_f32_e32 v120, 0x3d372713, v123
	v_mul_f32_e32 v133, v127, v133
	v_mul_f32_e32 v120, v123, v120
	v_fma_f32 v133, v127, v133, v127
	v_fma_f32 v120, v123, v120, v123
	v_mul_f32_e32 v133, 0x3fcc422a, v133
	v_mul_f32_e32 v120, 0x3fcc422a, v120
	v_mul_f32_e32 v133, 0xbfb8aa3b, v133
	v_mul_f32_e32 v120, 0xbfb8aa3b, v120
	v_exp_f32_e32 v133, v133
	v_exp_f32_e32 v120, v120
	v_add_f32_e32 v133, 1.0, v133
	v_add_f32_e32 v120, 1.0, v120
	v_rcp_f32_e32 v151, v133
	v_rcp_f32_e32 v153, v120
	v_pk_mul_f32 v[126:127], v[126:127], v[150:151]
	v_pk_mul_f32 v[122:123], v[122:123], v[152:153]

; __device__ __forceinline__ unsigned cvt_pk_bf16(float lo, float hi) { unsigned r; asm volatile("v_cvt_pk_bf16_f32 %0, %1, %2" : "=v"(r) : "v"(lo), "v"(hi)); return r; }
; __device__ __forceinline__ float gelu_t(float x) { const float z = 1.5957691216f * (x + 0.044715f * x * x * x); return x * sigm(z); }
; #define EPI_FOR_ROWS() _Pragma("unroll") for (int ai = 0; ai < 2; ++ai) _Pragma("unroll") for (int m = 0; m < 4; ++m)
; __device__ __forceinline__ float row_rstd(const float* ssq, int row, int fq) {
;     const f32x4 q = *(const f32x4*)(ssq + (size_t)row * 16 + 4 * fq); float s = (q[0] + q[1]) + (q[2] + q[3]);
;     s += __shfl_xor(s, 16); s += __shfl_xor(s, 32); return rsqrtf(s * (1.0f / 1024.0f) + EPS);
; }
;     __device__ __forceinline__ void operator()(const f32x4 (&acc)[2][2][4][2], const Unit& u, int wr, int wc, int fr, int fq) const {
;     ...
;         EPI_FOR_ROWS() {
;             const int row = row0 + ai * 128 + m * 16; const float rs = row_rstd(ssq, row, fq);
; #pragma unroll
;             for (int bj = 0; bj < 2; ++bj) { const int col = col0 + bj * 128; f32x4 v0 = acc[ai][bj][m][0] * rs, v1 = acc[ai][bj][m][1] * rs;
;                 if (u.pn >= 2) {
; #pragma unroll
;                     for (int e = 0; e < 4; ++e) { v0[e] = gelu_t(v0[e]); v1[e] = gelu_t(v1[e]); } }
;                 u32x4 w; w.x = cvt_pk_bf16(v0[0], v0[1]); w.y = cvt_pk_bf16(v0[2], v0[3]); w.z = cvt_pk_bf16(v1[0], v1[1]); w.w = cvt_pk_bf16(v1[2], v1[3]);
;                 *(u32x4*)(proj + (size_t)row * 1536 + col) = w; }
.LBB0_240:
	v_cvt_pk_bf16_f32 v116, v116, v117
	v_cvt_pk_bf16_f32 v117, v118, v119
	v_cvt_pk_bf16_f32 v118, v112, v113
	v_or_b32_e32 v112, 16, v130
	v_ashrrev_i32_e32 v113, 31, v112
	v_cvt_pk_bf16_f32 v119, v114, v115
	v_lshlrev_b64 v[114:115], 6, v[112:113]
	global_store_dwordx4 v[122:123], v[116:119], off offset:256
	v_lshl_add_u64 v[114:115], v[128:129], 0, v[114:115]
	v_mov_b32_e32 v114, v166
	v_mov_b32_e32 v115, v167
	v_mov_b32_e32 v116, v168
	v_mov_b32_e32 v117, v169
	s_and_b64 vcc, exec, s[8:9]
	v_mov_b32_e32 v118, v115
	v_mov_b32_e32 v119, v116
	v_mov_b32_e32 v115, v117
	v_pk_add_f32 v[114:115], v[118:119], v[114:115]
	s_nop 0
	v_add_f32_e32 v113, v114, v115
	ds_bpermute_b32 v114, v131, v113
	s_waitcnt lgkmcnt(0)
	v_add_f32_e32 v113, v113, v114
	ds_bpermute_b32 v114, v147, v113
	s_waitcnt lgkmcnt(0)
	v_add_f32_e32 v113, v113, v114
	v_fmamk_f32 v113, v113, 0x3a800000, v208
	v_mul_f32_e32 v114, 0x4b800000, v113
	v_cmp_gt_f32_e64 s[10:11], s44, v113
	s_nop 1
	v_cndmask_b32_e64 v113, v113, v114, s[10:11]
	v_rsq_f32_e32 v113, v113
	s_nop 0
	v_mul_f32_e32 v114, 0x45800000, v113
	v_cndmask_b32_e64 v114, v113, v114, s[10:11]
	v_pk_mul_f32 v[110:111], v[110:111], v[114:115] op_sel_hi:[1,0]
	v_pk_mul_f32 v[108:109], v[108:109], v[114:115] op_sel_hi:[1,0]
	v_pk_mul_f32 v[106:107], v[106:107], v[114:115] op_sel_hi:[1,0]
	v_pk_mul_f32 v[104:105], v[104:105], v[114:115] op_sel_hi:[1,0]
	s_cbranch_vccnz .LBB0_242
	v_mul_f32_e32 v113, 0x3d372713, v108
	v_mul_f32_e32 v113, v108, v113
	v_fma_f32 v113, v108, v113, v108
	v_mul_f32_e32 v113, 0x3fcc422a, v113
	v_mul_f32_e32 v113, 0xbfb8aa3b, v113
	v_exp_f32_e32 v113, v113
	v_mov_b32_e32 v115, v109
	v_add_f32_e32 v113, 1.0, v113
	v_rcp_f32_e32 v116, v113
	v_mul_f32_e32 v113, 0x3d372713, v104
	v_mul_f32_e32 v113, v104, v113
	v_fma_f32 v113, v104, v113, v104
	v_mul_f32_e32 v113, 0x3fcc422a, v113
	v_mul_f32_e32 v113, 0xbfb8aa3b, v113
	v_exp_f32_e32 v113, v113
	s_nop 0
	v_add_f32_e32 v113, 1.0, v113
	v_rcp_f32_e32 v118, v113
	v_mul_f32_e32 v113, 0x3d372713, v109
	v_mul_f32_e32 v113, v109, v113
	v_fmac_f32_e32 v115, v115, v113
	v_mul_f32_e32 v113, 0x3fcc422a, v115
	v_mul_f32_e32 v113, 0xbfb8aa3b, v113
	v_exp_f32_e32 v113, v113
	v_mov_b32_e32 v115, v105
	v_add_f32_e32 v113, 1.0, v113
	v_rcp_f32_e32 v117, v113
	v_mul_f32_e32 v113, 0x3d372713, v105
	v_mul_f32_e32 v113, v105, v113
	v_fmac_f32_e32 v115, v115, v113
	v_mul_f32_e32 v113, 0x3fcc422a, v115
	v_mul_f32_e32 v113, 0xbfb8aa3b, v113
	v_exp_f32_e32 v113, v113
	v_pk_mul_f32 v[108:109], v[108:109], v[116:117]
	v_add_f32_e32 v113, 1.0, v113
	v_rcp_f32_e32 v119, v113
	v_mul_f32_e32 v113, 0x3d372713, v110
	v_mul_f32_e32 v113, v110, v113
	v_fma_f32 v113, v110, v113, v110
	v_mul_f32_e32 v113, 0x3fcc422a, v113
	v_mul_f32_e32 v113, 0xbfb8aa3b, v113
	v_exp_f32_e32 v113, v113
	v_pk_mul_f32 v[104:105], v[104:105], v[118:119]
	v_add_f32_e32 v113, 1.0, v113
	v_rcp_f32_e32 v122, v113
	v_mul_f32_e32 v113, 0x3d372713, v106
	v_mul_f32_e32 v113, v106, v113
	v_fma_f32 v113, v106, v113, v106
	v_mul_f32_e32 v113, 0x3fcc422a, v113
	v_mul_f32_e32 v113, 0xbfb8aa3b, v113
	v_exp_f32_e32 v113, v113
	s_nop 0
	v_add_f32_e32 v113, 1.0, v113
	v_rcp_f32_e32 v124, v113
	v_mul_f32_e32 v113, 0x3d372713, v111
	v_mul_f32_e32 v113, v111, v113
	v_fma_f32 v113, v111, v113, v111
	v_mul_f32_e32 v113, 0x3fcc422a, v113
	v_mul_f32_e32 v113, 0xbfb8aa3b, v113
	v_exp_f32_e32 v113, v113
	s_nop 0
	v_add_f32_e32 v113, 1.0, v113
	v_rcp_f32_e32 v123, v113
	v_mul_f32_e32 v113, 0x3d372713, v107
	v_mul_f32_e32 v113, v107, v113
	v_fma_f32 v113, v107, v113, v107
	v_mul_f32_e32 v113, 0x3fcc422a, v113
	v_mul_f32_e32 v113, 0xbfb8aa3b, v113
	v_exp_f32_e32 v113, v113
	v_pk_mul_f32 v[110:111], v[110:111], v[122:123]
	v_add_f32_e32 v113, 1.0, v113
	v_rcp_f32_e32 v125, v113
	s_nop 0
	v_pk_mul_f32 v[106:107], v[106:107], v[124:125]

; __device__ __forceinline__ unsigned cvt_pk_bf16(float lo, float hi) { unsigned r; asm volatile("v_cvt_pk_bf16_f32 %0, %1, %2" : "=v"(r) : "v"(lo), "v"(hi)); return r; }
; __device__ __forceinline__ float gelu_t(float x) { const float z = 1.5957691216f * (x + 0.044715f * x * x * x); return x * sigm(z); }
; #define EPI_FOR_ROWS() _Pragma("unroll") for (int ai = 0; ai < 2; ++ai) _Pragma("unroll") for (int m = 0; m < 4; ++m)
; __device__ __forceinline__ float row_rstd(const float* ssq, int row, int fq) {
;     const f32x4 q = *(const f32x4*)(ssq + (size_t)row * 16 + 4 * fq); float s = (q[0] + q[1]) + (q[2] + q[3]);
;     s += __shfl_xor(s, 16); s += __shfl_xor(s, 32); return rsqrtf(s * (1.0f / 1024.0f) + EPS);
; }
;     __device__ __forceinline__ void operator()(const f32x4 (&acc)[2][2][4][2], const Unit& u, int wr, int wc, int fr, int fq) const {
;     ...
;         EPI_FOR_ROWS() {
;             const int row = row0 + ai * 128 + m * 16; const float rs = row_rstd(ssq, row, fq);
; #pragma unroll
;             for (int bj = 0; bj < 2; ++bj) { const int col = col0 + bj * 128; f32x4 v0 = acc[ai][bj][m][0] * rs, v1 = acc[ai][bj][m][1] * rs;
;                 if (u.pn >= 2) {
; #pragma unroll
;                     for (int e = 0; e < 4; ++e) { v0[e] = gelu_t(v0[e]); v1[e] = gelu_t(v1[e]); } }
;                 u32x4 w; w.x = cvt_pk_bf16(v0[0], v0[1]); w.y = cvt_pk_bf16(v0[2], v0[3]); w.z = cvt_pk_bf16(v1[0], v1[1]); w.w = cvt_pk_bf16(v1[2], v1[3]);
;                 *(u32x4*)(proj + (size_t)row * 1536 + col) = w; }
.LBB0_244:
	v_cvt_pk_bf16_f32 v100, v100, v101
	v_cvt_pk_bf16_f32 v101, v102, v103
	v_cvt_pk_bf16_f32 v102, v96, v97
	v_or_b32_e32 v96, 32, v130
	v_ashrrev_i32_e32 v97, 31, v96
	v_cvt_pk_bf16_f32 v103, v98, v99
	v_lshlrev_b64 v[98:99], 6, v[96:97]
	global_store_dwordx4 v[104:105], v[100:103], off offset:256
	v_lshl_add_u64 v[98:99], v[128:129], 0, v[98:99]
	v_mov_b32_e32 v98, v178
	v_mov_b32_e32 v99, v179
	v_mov_b32_e32 v100, v180
	v_mov_b32_e32 v101, v181
	s_and_b64 vcc, exec, s[8:9]
	v_mov_b32_e32 v102, v99
	v_mov_b32_e32 v103, v100
	v_mov_b32_e32 v99, v101
	v_pk_add_f32 v[98:99], v[102:103], v[98:99]
	s_nop 0
	v_add_f32_e32 v97, v98, v99
	ds_bpermute_b32 v98, v131, v97
	s_waitcnt lgkmcnt(0)
	v_add_f32_e32 v97, v97, v98
	ds_bpermute_b32 v98, v147, v97
	s_waitcnt lgkmcnt(0)
	v_add_f32_e32 v97, v97, v98
	v_fmamk_f32 v97, v97, 0x3a800000, v208
	v_mul_f32_e32 v98, 0x4b800000, v97
	v_cmp_gt_f32_e64 s[10:11], s44, v97
	s_nop 1
	v_cndmask_b32_e64 v97, v97, v98, s[10:11]
	v_rsq_f32_e32 v97, v97
	s_nop 0
	v_mul_f32_e32 v98, 0x45800000, v97
	v_cndmask_b32_e64 v98, v97, v98, s[10:11]
	v_pk_mul_f32 v[94:95], v[94:95], v[98:99] op_sel_hi:[1,0]
	v_pk_mul_f32 v[92:93], v[92:93], v[98:99] op_sel_hi:[1,0]
	v_pk_mul_f32 v[90:91], v[90:91], v[98:99] op_sel_hi:[1,0]
	v_pk_mul_f32 v[88:89], v[88:89], v[98:99] op_sel_hi:[1,0]
	s_cbranch_vccnz .LBB0_246
	v_mul_f32_e32 v97, 0x3d372713, v92
	v_mul_f32_e32 v97, v92, v97
	v_fma_f32 v97, v92, v97, v92
	v_mul_f32_e32 v97, 0x3fcc422a, v97
	v_mul_f32_e32 v97, 0xbfb8aa3b, v97
	v_exp_f32_e32 v97, v97
	v_mov_b32_e32 v99, v93
	v_add_f32_e32 v97, 1.0, v97
	v_rcp_f32_e32 v100, v97
	v_mul_f32_e32 v97, 0x3d372713, v88
	v_mul_f32_e32 v97, v88, v97
	v_fma_f32 v97, v88, v97, v88
	v_mul_f32_e32 v97, 0x3fcc422a, v97
	v_mul_f32_e32 v97, 0xbfb8aa3b, v97
	v_exp_f32_e32 v97, v97
	s_nop 0
	v_add_f32_e32 v97, 1.0, v97
	v_rcp_f32_e32 v102, v97
	v_mul_f32_e32 v97, 0x3d372713, v93
	v_mul_f32_e32 v97, v93, v97
	v_fmac_f32_e32 v99, v99, v97
	v_mul_f32_e32 v97, 0x3fcc422a, v99
	v_mul_f32_e32 v97, 0xbfb8aa3b, v97
	v_exp_f32_e32 v97, v97
	v_mov_b32_e32 v99, v89
	v_add_f32_e32 v97, 1.0, v97
	v_rcp_f32_e32 v101, v97
	v_mul_f32_e32 v97, 0x3d372713, v89
	v_mul_f32_e32 v97, v89, v97
	v_fmac_f32_e32 v99, v99, v97
	v_mul_f32_e32 v97, 0x3fcc422a, v99
	v_mul_f32_e32 v97, 0xbfb8aa3b, v97
	v_exp_f32_e32 v97, v97
	v_pk_mul_f32 v[92:93], v[92:93], v[100:101]
	v_add_f32_e32 v97, 1.0, v97
	v_rcp_f32_e32 v103, v97
	v_mul_f32_e32 v97, 0x3d372713, v94
	v_mul_f32_e32 v97, v94, v97
	v_fma_f32 v97, v94, v97, v94
	v_mul_f32_e32 v97, 0x3fcc422a, v97
	v_mul_f32_e32 v97, 0xbfb8aa3b, v97
	v_exp_f32_e32 v97, v97
	v_pk_mul_f32 v[88:89], v[88:89], v[102:103]
	v_add_f32_e32 v97, 1.0, v97
	v_rcp_f32_e32 v104, v97
	v_mul_f32_e32 v97, 0x3d372713, v90
	v_mul_f32_e32 v97, v90, v97
	v_fma_f32 v97, v90, v97, v90
	v_mul_f32_e32 v97, 0x3fcc422a, v97
	v_mul_f32_e32 v97, 0xbfb8aa3b, v97
	v_exp_f32_e32 v97, v97
	s_nop 0
	v_add_f32_e32 v97, 1.0, v97
	v_rcp_f32_e32 v106, v97
	v_mul_f32_e32 v97, 0x3d372713, v95
	v_mul_f32_e32 v97, v95, v97
	v_fma_f32 v97, v95, v97, v95
	v_mul_f32_e32 v97, 0x3fcc422a, v97
	v_mul_f32_e32 v97, 0xbfb8aa3b, v97
	v_exp_f32_e32 v97, v97
	s_nop 0
	v_add_f32_e32 v97, 1.0, v97
	v_rcp_f32_e32 v105, v97
	v_mul_f32_e32 v97, 0x3d372713, v91
	v_mul_f32_e32 v97, v91, v97
	v_fma_f32 v97, v91, v97, v91
	v_mul_f32_e32 v97, 0x3fcc422a, v97
	v_mul_f32_e32 v97, 0xbfb8aa3b, v97
	v_exp_f32_e32 v97, v97
	v_pk_mul_f32 v[94:95], v[94:95], v[104:105]
	v_add_f32_e32 v97, 1.0, v97
	v_rcp_f32_e32 v107, v97
	s_nop 0
	v_pk_mul_f32 v[90:91], v[90:91], v[106:107]

; __device__ __forceinline__ unsigned cvt_pk_bf16(float lo, float hi) { unsigned r; asm volatile("v_cvt_pk_bf16_f32 %0, %1, %2" : "=v"(r) : "v"(lo), "v"(hi)); return r; }
; __device__ __forceinline__ float gelu_t(float x) { const float z = 1.5957691216f * (x + 0.044715f * x * x * x); return x * sigm(z); }
; #define EPI_FOR_ROWS() _Pragma("unroll") for (int ai = 0; ai < 2; ++ai) _Pragma("unroll") for (int m = 0; m < 4; ++m)
; __device__ __forceinline__ float row_rstd(const float* ssq, int row, int fq) {
;     const f32x4 q = *(const f32x4*)(ssq + (size_t)row * 16 + 4 * fq); float s = (q[0] + q[1]) + (q[2] + q[3]);
;     s += __shfl_xor(s, 16); s += __shfl_xor(s, 32); return rsqrtf(s * (1.0f / 1024.0f) + EPS);
; }
;     __device__ __forceinline__ void operator()(const f32x4 (&acc)[2][2][4][2], const Unit& u, int wr, int wc, int fr, int fq) const {
;     ...
;         EPI_FOR_ROWS() {
;             const int row = row0 + ai * 128 + m * 16; const float rs = row_rstd(ssq, row, fq);
; #pragma unroll
;             for (int bj = 0; bj < 2; ++bj) { const int col = col0 + bj * 128; f32x4 v0 = acc[ai][bj][m][0] * rs, v1 = acc[ai][bj][m][1] * rs;
;                 if (u.pn >= 2) {
; #pragma unroll
;                     for (int e = 0; e < 4; ++e) { v0[e] = gelu_t(v0[e]); v1[e] = gelu_t(v1[e]); } }
;                 u32x4 w; w.x = cvt_pk_bf16(v0[0], v0[1]); w.y = cvt_pk_bf16(v0[2], v0[3]); w.z = cvt_pk_bf16(v1[0], v1[1]); w.w = cvt_pk_bf16(v1[2], v1[3]);
;                 *(u32x4*)(proj + (size_t)row * 1536 + col) = w; }
.LBB0_248:
	v_cvt_pk_bf16_f32 v84, v84, v85
	v_cvt_pk_bf16_f32 v85, v86, v87
	v_cvt_pk_bf16_f32 v86, v80, v81
	v_or_b32_e32 v80, 48, v130
	v_ashrrev_i32_e32 v81, 31, v80
	v_cvt_pk_bf16_f32 v87, v82, v83
	v_lshlrev_b64 v[82:83], 6, v[80:81]
	global_store_dwordx4 v[88:89], v[84:87], off offset:256
	v_lshl_add_u64 v[82:83], v[128:129], 0, v[82:83]
	v_mov_b32_e32 v82, v182
	v_mov_b32_e32 v83, v183
	v_mov_b32_e32 v84, v184
	v_mov_b32_e32 v85, v185
	s_and_b64 vcc, exec, s[8:9]
	v_mov_b32_e32 v86, v83
	v_mov_b32_e32 v87, v84
	v_mov_b32_e32 v83, v85
	v_pk_add_f32 v[82:83], v[86:87], v[82:83]
	s_nop 0
	v_add_f32_e32 v81, v82, v83
	ds_bpermute_b32 v82, v131, v81
	s_waitcnt lgkmcnt(0)
	v_add_f32_e32 v81, v81, v82
	ds_bpermute_b32 v82, v147, v81
	s_waitcnt lgkmcnt(0)
	v_add_f32_e32 v81, v81, v82
	v_fmamk_f32 v81, v81, 0x3a800000, v208
	v_mul_f32_e32 v82, 0x4b800000, v81
	v_cmp_gt_f32_e64 s[10:11], s44, v81
	s_nop 1
	v_cndmask_b32_e64 v81, v81, v82, s[10:11]
	v_rsq_f32_e32 v81, v81
	s_nop 0
	v_mul_f32_e32 v82, 0x45800000, v81
	v_cndmask_b32_e64 v82, v81, v82, s[10:11]
	v_pk_mul_f32 v[78:79], v[78:79], v[82:83] op_sel_hi:[1,0]
	v_pk_mul_f32 v[76:77], v[76:77], v[82:83] op_sel_hi:[1,0]
	v_pk_mul_f32 v[74:75], v[74:75], v[82:83] op_sel_hi:[1,0]
	v_pk_mul_f32 v[72:73], v[72:73], v[82:83] op_sel_hi:[1,0]
	s_cbranch_vccnz .LBB0_250
	v_mul_f32_e32 v81, 0x3d372713, v76
	v_mul_f32_e32 v81, v76, v81
	v_fma_f32 v81, v76, v81, v76
	v_mul_f32_e32 v81, 0x3fcc422a, v81
	v_mul_f32_e32 v81, 0xbfb8aa3b, v81
	v_exp_f32_e32 v81, v81
	v_mov_b32_e32 v83, v77
	v_add_f32_e32 v81, 1.0, v81
	v_rcp_f32_e32 v84, v81
	v_mul_f32_e32 v81, 0x3d372713, v72
	v_mul_f32_e32 v81, v72, v81
	v_fma_f32 v81, v72, v81, v72
	v_mul_f32_e32 v81, 0x3fcc422a, v81
	v_mul_f32_e32 v81, 0xbfb8aa3b, v81
	v_exp_f32_e32 v81, v81
	s_nop 0
	v_add_f32_e32 v81, 1.0, v81
	v_rcp_f32_e32 v86, v81
	v_mul_f32_e32 v81, 0x3d372713, v77
	v_mul_f32_e32 v81, v77, v81
	v_fmac_f32_e32 v83, v83, v81
	v_mul_f32_e32 v81, 0x3fcc422a, v83
	v_mul_f32_e32 v81, 0xbfb8aa3b, v81
	v_exp_f32_e32 v81, v81
	v_mov_b32_e32 v83, v73
	v_add_f32_e32 v81, 1.0, v81
	v_rcp_f32_e32 v85, v81
	v_mul_f32_e32 v81, 0x3d372713, v73
	v_mul_f32_e32 v81, v73, v81
	v_fmac_f32_e32 v83, v83, v81
	v_mul_f32_e32 v81, 0x3fcc422a, v83
	v_mul_f32_e32 v81, 0xbfb8aa3b, v81
	v_exp_f32_e32 v81, v81
	v_pk_mul_f32 v[76:77], v[76:77], v[84:85]
	v_add_f32_e32 v81, 1.0, v81
	v_rcp_f32_e32 v87, v81
	v_mul_f32_e32 v81, 0x3d372713, v78
	v_mul_f32_e32 v81, v78, v81
	v_fma_f32 v81, v78, v81, v78
	v_mul_f32_e32 v81, 0x3fcc422a, v81
	v_mul_f32_e32 v81, 0xbfb8aa3b, v81
	v_exp_f32_e32 v81, v81
	v_pk_mul_f32 v[72:73], v[72:73], v[86:87]
	v_add_f32_e32 v81, 1.0, v81
	v_rcp_f32_e32 v88, v81
	v_mul_f32_e32 v81, 0x3d372713, v74
	v_mul_f32_e32 v81, v74, v81
	v_fma_f32 v81, v74, v81, v74
	v_mul_f32_e32 v81, 0x3fcc422a, v81
	v_mul_f32_e32 v81, 0xbfb8aa3b, v81
	v_exp_f32_e32 v81, v81
	s_nop 0
	v_add_f32_e32 v81, 1.0, v81
	v_rcp_f32_e32 v90, v81
	v_mul_f32_e32 v81, 0x3d372713, v79
	v_mul_f32_e32 v81, v79, v81
	v_fma_f32 v81, v79, v81, v79
	v_mul_f32_e32 v81, 0x3fcc422a, v81
	v_mul_f32_e32 v81, 0xbfb8aa3b, v81
	v_exp_f32_e32 v81, v81
	s_nop 0
	v_add_f32_e32 v81, 1.0, v81
	v_rcp_f32_e32 v89, v81
	v_mul_f32_e32 v81, 0x3d372713, v75
	v_mul_f32_e32 v81, v75, v81
	v_fma_f32 v81, v75, v81, v75
	v_mul_f32_e32 v81, 0x3fcc422a, v81
	v_mul_f32_e32 v81, 0xbfb8aa3b, v81
	v_exp_f32_e32 v81, v81
	v_pk_mul_f32 v[78:79], v[78:79], v[88:89]
	v_add_f32_e32 v81, 1.0, v81
	v_rcp_f32_e32 v91, v81
	s_nop 0
	v_pk_mul_f32 v[74:75], v[74:75], v[90:91]

; __device__ __forceinline__ unsigned cvt_pk_bf16(float lo, float hi) { unsigned r; asm volatile("v_cvt_pk_bf16_f32 %0, %1, %2" : "=v"(r) : "v"(lo), "v"(hi)); return r; }
; __device__ __forceinline__ float gelu_t(float x) { const float z = 1.5957691216f * (x + 0.044715f * x * x * x); return x * sigm(z); }
; #define EPI_FOR_ROWS() _Pragma("unroll") for (int ai = 0; ai < 2; ++ai) _Pragma("unroll") for (int m = 0; m < 4; ++m)
; __device__ __forceinline__ float row_rstd(const float* ssq, int row, int fq) {
;     const f32x4 q = *(const f32x4*)(ssq + (size_t)row * 16 + 4 * fq); float s = (q[0] + q[1]) + (q[2] + q[3]);
;     s += __shfl_xor(s, 16); s += __shfl_xor(s, 32); return rsqrtf(s * (1.0f / 1024.0f) + EPS);
; }
;     __device__ __forceinline__ void operator()(const f32x4 (&acc)[2][2][4][2], const Unit& u, int wr, int wc, int fr, int fq) const {
;     ...
;         EPI_FOR_ROWS() {
;             const int row = row0 + ai * 128 + m * 16; const float rs = row_rstd(ssq, row, fq);
; #pragma unroll
;             for (int bj = 0; bj < 2; ++bj) { const int col = col0 + bj * 128; f32x4 v0 = acc[ai][bj][m][0] * rs, v1 = acc[ai][bj][m][1] * rs;
;                 if (u.pn >= 2) {
; #pragma unroll
;                     for (int e = 0; e < 4; ++e) { v0[e] = gelu_t(v0[e]); v1[e] = gelu_t(v1[e]); } }
;                 u32x4 w; w.x = cvt_pk_bf16(v0[0], v0[1]); w.y = cvt_pk_bf16(v0[2], v0[3]); w.z = cvt_pk_bf16(v1[0], v1[1]); w.w = cvt_pk_bf16(v1[2], v1[3]);
;                 *(u32x4*)(proj + (size_t)row * 1536 + col) = w; }
.LBB0_252:
	v_cvt_pk_bf16_f32 v68, v68, v69
	v_cvt_pk_bf16_f32 v69, v70, v71
	v_cvt_pk_bf16_f32 v70, v64, v65
	v_add_u32_e32 v64, 0x80, v130
	v_ashrrev_i32_e32 v65, 31, v64
	v_cvt_pk_bf16_f32 v71, v66, v67
	v_lshlrev_b64 v[66:67], 6, v[64:65]
	global_store_dwordx4 v[72:73], v[68:71], off offset:256
	v_lshl_add_u64 v[66:67], v[128:129], 0, v[66:67]
	v_mov_b32_e32 v66, v186
	v_mov_b32_e32 v67, v187
	v_mov_b32_e32 v68, v188
	v_mov_b32_e32 v69, v189
	s_and_b64 vcc, exec, s[8:9]
	v_mov_b32_e32 v70, v67
	v_mov_b32_e32 v71, v68
	v_mov_b32_e32 v67, v69
	v_pk_add_f32 v[66:67], v[70:71], v[66:67]
	s_nop 0
	v_add_f32_e32 v65, v66, v67
	ds_bpermute_b32 v66, v131, v65
	s_waitcnt lgkmcnt(0)
	v_add_f32_e32 v65, v65, v66
	ds_bpermute_b32 v66, v147, v65
	s_waitcnt lgkmcnt(0)
	v_add_f32_e32 v65, v65, v66
	v_fmamk_f32 v65, v65, 0x3a800000, v208
	v_mul_f32_e32 v66, 0x4b800000, v65
	v_cmp_gt_f32_e64 s[10:11], s44, v65
	s_nop 1
	v_cndmask_b32_e64 v65, v65, v66, s[10:11]
	v_rsq_f32_e32 v65, v65
	s_nop 0
	v_mul_f32_e32 v66, 0x45800000, v65
	v_cndmask_b32_e64 v66, v65, v66, s[10:11]
	v_pk_mul_f32 v[62:63], v[62:63], v[66:67] op_sel_hi:[1,0]
	v_pk_mul_f32 v[60:61], v[60:61], v[66:67] op_sel_hi:[1,0]
	v_pk_mul_f32 v[58:59], v[58:59], v[66:67] op_sel_hi:[1,0]
	v_pk_mul_f32 v[56:57], v[56:57], v[66:67] op_sel_hi:[1,0]
	s_cbranch_vccnz .LBB0_254
	v_mul_f32_e32 v65, 0x3d372713, v60
	v_mul_f32_e32 v65, v60, v65
	v_fma_f32 v65, v60, v65, v60
	v_mul_f32_e32 v65, 0x3fcc422a, v65
	v_mul_f32_e32 v65, 0xbfb8aa3b, v65
	v_exp_f32_e32 v65, v65
	v_mov_b32_e32 v67, v61
	v_add_f32_e32 v65, 1.0, v65
	v_rcp_f32_e32 v68, v65
	v_mul_f32_e32 v65, 0x3d372713, v56
	v_mul_f32_e32 v65, v56, v65
	v_fma_f32 v65, v56, v65, v56
	v_mul_f32_e32 v65, 0x3fcc422a, v65
	v_mul_f32_e32 v65, 0xbfb8aa3b, v65
	v_exp_f32_e32 v65, v65
	s_nop 0
	v_add_f32_e32 v65, 1.0, v65
	v_rcp_f32_e32 v70, v65
	v_mul_f32_e32 v65, 0x3d372713, v61
	v_mul_f32_e32 v65, v61, v65
	v_fmac_f32_e32 v67, v67, v65
	v_mul_f32_e32 v65, 0x3fcc422a, v67
	v_mul_f32_e32 v65, 0xbfb8aa3b, v65
	v_exp_f32_e32 v65, v65
	v_mov_b32_e32 v67, v57
	v_add_f32_e32 v65, 1.0, v65
	v_rcp_f32_e32 v69, v65
	v_mul_f32_e32 v65, 0x3d372713, v57
	v_mul_f32_e32 v65, v57, v65
	v_fmac_f32_e32 v67, v67, v65
	v_mul_f32_e32 v65, 0x3fcc422a, v67
	v_mul_f32_e32 v65, 0xbfb8aa3b, v65
	v_exp_f32_e32 v65, v65
	v_pk_mul_f32 v[60:61], v[60:61], v[68:69]
	v_add_f32_e32 v65, 1.0, v65
	v_rcp_f32_e32 v71, v65
	v_mul_f32_e32 v65, 0x3d372713, v62
	v_mul_f32_e32 v65, v62, v65
	v_fma_f32 v65, v62, v65, v62
	v_mul_f32_e32 v65, 0x3fcc422a, v65
	v_mul_f32_e32 v65, 0xbfb8aa3b, v65
	v_exp_f32_e32 v65, v65
	v_pk_mul_f32 v[56:57], v[56:57], v[70:71]
	v_add_f32_e32 v65, 1.0, v65
	v_rcp_f32_e32 v72, v65
	v_mul_f32_e32 v65, 0x3d372713, v58
	v_mul_f32_e32 v65, v58, v65
	v_fma_f32 v65, v58, v65, v58
	v_mul_f32_e32 v65, 0x3fcc422a, v65
	v_mul_f32_e32 v65, 0xbfb8aa3b, v65
	v_exp_f32_e32 v65, v65
	s_nop 0
	v_add_f32_e32 v65, 1.0, v65
	v_rcp_f32_e32 v74, v65
	v_mul_f32_e32 v65, 0x3d372713, v63
	v_mul_f32_e32 v65, v63, v65
	v_fma_f32 v65, v63, v65, v63
	v_mul_f32_e32 v65, 0x3fcc422a, v65
	v_mul_f32_e32 v65, 0xbfb8aa3b, v65
	v_exp_f32_e32 v65, v65
	s_nop 0
	v_add_f32_e32 v65, 1.0, v65
	v_rcp_f32_e32 v73, v65
	v_mul_f32_e32 v65, 0x3d372713, v59
	v_mul_f32_e32 v65, v59, v65
	v_fma_f32 v65, v59, v65, v59
	v_mul_f32_e32 v65, 0x3fcc422a, v65
	v_mul_f32_e32 v65, 0xbfb8aa3b, v65
	v_exp_f32_e32 v65, v65
	v_pk_mul_f32 v[62:63], v[62:63], v[72:73]
	v_add_f32_e32 v65, 1.0, v65
	v_rcp_f32_e32 v75, v65
	s_nop 0
	v_pk_mul_f32 v[58:59], v[58:59], v[74:75]

; __device__ __forceinline__ unsigned cvt_pk_bf16(float lo, float hi) { unsigned r; asm volatile("v_cvt_pk_bf16_f32 %0, %1, %2" : "=v"(r) : "v"(lo), "v"(hi)); return r; }
; __device__ __forceinline__ float gelu_t(float x) { const float z = 1.5957691216f * (x + 0.044715f * x * x * x); return x * sigm(z); }
; #define EPI_FOR_ROWS() _Pragma("unroll") for (int ai = 0; ai < 2; ++ai) _Pragma("unroll") for (int m = 0; m < 4; ++m)
; __device__ __forceinline__ float row_rstd(const float* ssq, int row, int fq) {
;     const f32x4 q = *(const f32x4*)(ssq + (size_t)row * 16 + 4 * fq); float s = (q[0] + q[1]) + (q[2] + q[3]);
;     s += __shfl_xor(s, 16); s += __shfl_xor(s, 32); return rsqrtf(s * (1.0f / 1024.0f) + EPS);
; }
;     __device__ __forceinline__ void operator()(const f32x4 (&acc)[2][2][4][2], const Unit& u, int wr, int wc, int fr, int fq) const {
;     ...
;         EPI_FOR_ROWS() {
;             const int row = row0 + ai * 128 + m * 16; const float rs = row_rstd(ssq, row, fq);
; #pragma unroll
;             for (int bj = 0; bj < 2; ++bj) { const int col = col0 + bj * 128; f32x4 v0 = acc[ai][bj][m][0] * rs, v1 = acc[ai][bj][m][1] * rs;
;                 if (u.pn >= 2) {
; #pragma unroll
;                     for (int e = 0; e < 4; ++e) { v0[e] = gelu_t(v0[e]); v1[e] = gelu_t(v1[e]); } }
;                 u32x4 w; w.x = cvt_pk_bf16(v0[0], v0[1]); w.y = cvt_pk_bf16(v0[2], v0[3]); w.z = cvt_pk_bf16(v1[0], v1[1]); w.w = cvt_pk_bf16(v1[2], v1[3]);
;                 *(u32x4*)(proj + (size_t)row * 1536 + col) = w; }
.LBB0_256:
	v_cvt_pk_bf16_f32 v52, v52, v53
	v_cvt_pk_bf16_f32 v53, v54, v55
	v_cvt_pk_bf16_f32 v54, v48, v49
	v_add_u32_e32 v48, 0x90, v130
	v_ashrrev_i32_e32 v49, 31, v48
	v_cvt_pk_bf16_f32 v55, v50, v51
	v_lshlrev_b64 v[50:51], 6, v[48:49]
	global_store_dwordx4 v[56:57], v[52:55], off offset:256
	v_lshl_add_u64 v[50:51], v[128:129], 0, v[50:51]
	v_mov_b32_e32 v50, v190
	v_mov_b32_e32 v51, v191
	v_mov_b32_e32 v52, v192
	v_mov_b32_e32 v53, v193
	s_and_b64 vcc, exec, s[8:9]
	v_mov_b32_e32 v54, v51
	v_mov_b32_e32 v55, v52
	v_mov_b32_e32 v51, v53
	v_pk_add_f32 v[50:51], v[54:55], v[50:51]
	s_nop 0
	v_add_f32_e32 v49, v50, v51
	ds_bpermute_b32 v50, v131, v49
	s_waitcnt lgkmcnt(0)
	v_add_f32_e32 v49, v49, v50
	ds_bpermute_b32 v50, v147, v49
	s_waitcnt lgkmcnt(0)
	v_add_f32_e32 v49, v49, v50
	v_fmamk_f32 v49, v49, 0x3a800000, v208
	v_mul_f32_e32 v50, 0x4b800000, v49
	v_cmp_gt_f32_e64 s[10:11], s44, v49
	s_nop 1
	v_cndmask_b32_e64 v49, v49, v50, s[10:11]
	v_rsq_f32_e32 v49, v49
	s_nop 0
	v_mul_f32_e32 v50, 0x45800000, v49
	v_cndmask_b32_e64 v50, v49, v50, s[10:11]
	v_pk_mul_f32 v[46:47], v[46:47], v[50:51] op_sel_hi:[1,0]
	v_pk_mul_f32 v[44:45], v[44:45], v[50:51] op_sel_hi:[1,0]
	v_pk_mul_f32 v[42:43], v[42:43], v[50:51] op_sel_hi:[1,0]
	v_pk_mul_f32 v[40:41], v[40:41], v[50:51] op_sel_hi:[1,0]
	s_cbranch_vccnz .LBB0_258
	v_mul_f32_e32 v49, 0x3d372713, v44
	v_mul_f32_e32 v49, v44, v49
	v_fma_f32 v49, v44, v49, v44
	v_mul_f32_e32 v49, 0x3fcc422a, v49
	v_mul_f32_e32 v49, 0xbfb8aa3b, v49
	v_exp_f32_e32 v49, v49
	v_mov_b32_e32 v51, v45
	v_add_f32_e32 v49, 1.0, v49
	v_rcp_f32_e32 v52, v49
	v_mul_f32_e32 v49, 0x3d372713, v40
	v_mul_f32_e32 v49, v40, v49
	v_fma_f32 v49, v40, v49, v40
	v_mul_f32_e32 v49, 0x3fcc422a, v49
	v_mul_f32_e32 v49, 0xbfb8aa3b, v49
	v_exp_f32_e32 v49, v49
	s_nop 0
	v_add_f32_e32 v49, 1.0, v49
	v_rcp_f32_e32 v54, v49
	v_mul_f32_e32 v49, 0x3d372713, v45
	v_mul_f32_e32 v49, v45, v49
	v_fmac_f32_e32 v51, v51, v49
	v_mul_f32_e32 v49, 0x3fcc422a, v51
	v_mul_f32_e32 v49, 0xbfb8aa3b, v49
	v_exp_f32_e32 v49, v49
	v_mov_b32_e32 v51, v41
	v_add_f32_e32 v49, 1.0, v49
	v_rcp_f32_e32 v53, v49
	v_mul_f32_e32 v49, 0x3d372713, v41
	v_mul_f32_e32 v49, v41, v49
	v_fmac_f32_e32 v51, v51, v49
	v_mul_f32_e32 v49, 0x3fcc422a, v51
	v_mul_f32_e32 v49, 0xbfb8aa3b, v49
	v_exp_f32_e32 v49, v49
	v_pk_mul_f32 v[44:45], v[44:45], v[52:53]
	v_add_f32_e32 v49, 1.0, v49
	v_rcp_f32_e32 v55, v49
	v_mul_f32_e32 v49, 0x3d372713, v46
	v_mul_f32_e32 v49, v46, v49
	v_fma_f32 v49, v46, v49, v46
	v_mul_f32_e32 v49, 0x3fcc422a, v49
	v_mul_f32_e32 v49, 0xbfb8aa3b, v49
	v_exp_f32_e32 v49, v49
	v_pk_mul_f32 v[40:41], v[40:41], v[54:55]
	v_add_f32_e32 v49, 1.0, v49
	v_rcp_f32_e32 v56, v49
	v_mul_f32_e32 v49, 0x3d372713, v42
	v_mul_f32_e32 v49, v42, v49
	v_fma_f32 v49, v42, v49, v42
	v_mul_f32_e32 v49, 0x3fcc422a, v49
	v_mul_f32_e32 v49, 0xbfb8aa3b, v49
	v_exp_f32_e32 v49, v49
	s_nop 0
	v_add_f32_e32 v49, 1.0, v49
	v_rcp_f32_e32 v58, v49
	v_mul_f32_e32 v49, 0x3d372713, v47
	v_mul_f32_e32 v49, v47, v49
	v_fma_f32 v49, v47, v49, v47
	v_mul_f32_e32 v49, 0x3fcc422a, v49
	v_mul_f32_e32 v49, 0xbfb8aa3b, v49
	v_exp_f32_e32 v49, v49
	s_nop 0
	v_add_f32_e32 v49, 1.0, v49
	v_rcp_f32_e32 v57, v49
	v_mul_f32_e32 v49, 0x3d372713, v43
	v_mul_f32_e32 v49, v43, v49
	v_fma_f32 v49, v43, v49, v43
	v_mul_f32_e32 v49, 0x3fcc422a, v49
	v_mul_f32_e32 v49, 0xbfb8aa3b, v49
	v_exp_f32_e32 v49, v49
	v_pk_mul_f32 v[46:47], v[46:47], v[56:57]
	v_add_f32_e32 v49, 1.0, v49
	v_rcp_f32_e32 v59, v49
	s_nop 0
	v_pk_mul_f32 v[42:43], v[42:43], v[58:59]

; __device__ __forceinline__ unsigned cvt_pk_bf16(float lo, float hi) { unsigned r; asm volatile("v_cvt_pk_bf16_f32 %0, %1, %2" : "=v"(r) : "v"(lo), "v"(hi)); return r; }
; __device__ __forceinline__ float gelu_t(float x) { const float z = 1.5957691216f * (x + 0.044715f * x * x * x); return x * sigm(z); }
; #define EPI_FOR_ROWS() _Pragma("unroll") for (int ai = 0; ai < 2; ++ai) _Pragma("unroll") for (int m = 0; m < 4; ++m)
; __device__ __forceinline__ float row_rstd(const float* ssq, int row, int fq) {
;     const f32x4 q = *(const f32x4*)(ssq + (size_t)row * 16 + 4 * fq); float s = (q[0] + q[1]) + (q[2] + q[3]);
;     s += __shfl_xor(s, 16); s += __shfl_xor(s, 32); return rsqrtf(s * (1.0f / 1024.0f) + EPS);
; }
;     __device__ __forceinline__ void operator()(const f32x4 (&acc)[2][2][4][2], const Unit& u, int wr, int wc, int fr, int fq) const {
;     ...
;         EPI_FOR_ROWS() {
;             const int row = row0 + ai * 128 + m * 16; const float rs = row_rstd(ssq, row, fq);
; #pragma unroll
;             for (int bj = 0; bj < 2; ++bj) { const int col = col0 + bj * 128; f32x4 v0 = acc[ai][bj][m][0] * rs, v1 = acc[ai][bj][m][1] * rs;
;                 if (u.pn >= 2) {
; #pragma unroll
;                     for (int e = 0; e < 4; ++e) { v0[e] = gelu_t(v0[e]); v1[e] = gelu_t(v1[e]); } }
;                 u32x4 w; w.x = cvt_pk_bf16(v0[0], v0[1]); w.y = cvt_pk_bf16(v0[2], v0[3]); w.z = cvt_pk_bf16(v1[0], v1[1]); w.w = cvt_pk_bf16(v1[2], v1[3]);
;                 *(u32x4*)(proj + (size_t)row * 1536 + col) = w; }
.LBB0_260:
	v_cvt_pk_bf16_f32 v36, v36, v37
	v_cvt_pk_bf16_f32 v37, v38, v39
	v_cvt_pk_bf16_f32 v38, v32, v33
	v_add_u32_e32 v32, 0xa0, v130
	v_ashrrev_i32_e32 v33, 31, v32
	v_cvt_pk_bf16_f32 v39, v34, v35
	v_lshlrev_b64 v[34:35], 6, v[32:33]
	global_store_dwordx4 v[40:41], v[36:39], off offset:256
	v_lshl_add_u64 v[34:35], v[128:129], 0, v[34:35]
	v_mov_b32_e32 v34, v194
	v_mov_b32_e32 v35, v195
	v_mov_b32_e32 v36, v196
	v_mov_b32_e32 v37, v197
	s_and_b64 vcc, exec, s[8:9]
	v_mov_b32_e32 v38, v35
	v_mov_b32_e32 v39, v36
	v_mov_b32_e32 v35, v37
	v_pk_add_f32 v[34:35], v[38:39], v[34:35]
	s_nop 0
	v_add_f32_e32 v33, v34, v35
	ds_bpermute_b32 v34, v131, v33
	s_waitcnt lgkmcnt(0)
	v_add_f32_e32 v33, v33, v34
	ds_bpermute_b32 v34, v147, v33
	s_waitcnt lgkmcnt(0)
	v_add_f32_e32 v33, v33, v34
	v_fmamk_f32 v33, v33, 0x3a800000, v208
	v_mul_f32_e32 v34, 0x4b800000, v33
	v_cmp_gt_f32_e64 s[10:11], s44, v33
	s_nop 1
	v_cndmask_b32_e64 v33, v33, v34, s[10:11]
	v_rsq_f32_e32 v33, v33
	s_nop 0
	v_mul_f32_e32 v34, 0x45800000, v33
	v_cndmask_b32_e64 v34, v33, v34, s[10:11]
	v_pk_mul_f32 v[30:31], v[30:31], v[34:35] op_sel_hi:[1,0]
	v_pk_mul_f32 v[28:29], v[28:29], v[34:35] op_sel_hi:[1,0]
	v_pk_mul_f32 v[26:27], v[26:27], v[34:35] op_sel_hi:[1,0]
	v_pk_mul_f32 v[24:25], v[24:25], v[34:35] op_sel_hi:[1,0]
	s_cbranch_vccnz .LBB0_262
	v_mul_f32_e32 v33, 0x3d372713, v28
	v_mul_f32_e32 v33, v28, v33
	v_fma_f32 v33, v28, v33, v28
	v_mul_f32_e32 v33, 0x3fcc422a, v33
	v_mul_f32_e32 v33, 0xbfb8aa3b, v33
	v_exp_f32_e32 v33, v33
	v_mov_b32_e32 v35, v29
	v_add_f32_e32 v33, 1.0, v33
	v_rcp_f32_e32 v36, v33
	v_mul_f32_e32 v33, 0x3d372713, v24
	v_mul_f32_e32 v33, v24, v33
	v_fma_f32 v33, v24, v33, v24
	v_mul_f32_e32 v33, 0x3fcc422a, v33
	v_mul_f32_e32 v33, 0xbfb8aa3b, v33
	v_exp_f32_e32 v33, v33
	s_nop 0
	v_add_f32_e32 v33, 1.0, v33
	v_rcp_f32_e32 v38, v33
	v_mul_f32_e32 v33, 0x3d372713, v29
	v_mul_f32_e32 v33, v29, v33
	v_fmac_f32_e32 v35, v35, v33
	v_mul_f32_e32 v33, 0x3fcc422a, v35
	v_mul_f32_e32 v33, 0xbfb8aa3b, v33
	v_exp_f32_e32 v33, v33
	v_mov_b32_e32 v35, v25
	v_add_f32_e32 v33, 1.0, v33
	v_rcp_f32_e32 v37, v33
	v_mul_f32_e32 v33, 0x3d372713, v25
	v_mul_f32_e32 v33, v25, v33
	v_fmac_f32_e32 v35, v35, v33
	v_mul_f32_e32 v33, 0x3fcc422a, v35
	v_mul_f32_e32 v33, 0xbfb8aa3b, v33
	v_exp_f32_e32 v33, v33
	v_pk_mul_f32 v[28:29], v[28:29], v[36:37]
	v_add_f32_e32 v33, 1.0, v33
	v_rcp_f32_e32 v39, v33
	v_mul_f32_e32 v33, 0x3d372713, v30
	v_mul_f32_e32 v33, v30, v33
	v_fma_f32 v33, v30, v33, v30
	v_mul_f32_e32 v33, 0x3fcc422a, v33
	v_mul_f32_e32 v33, 0xbfb8aa3b, v33
	v_exp_f32_e32 v33, v33
	v_pk_mul_f32 v[24:25], v[24:25], v[38:39]
	v_add_f32_e32 v33, 1.0, v33
	v_rcp_f32_e32 v40, v33
	v_mul_f32_e32 v33, 0x3d372713, v26
	v_mul_f32_e32 v33, v26, v33
	v_fma_f32 v33, v26, v33, v26
	v_mul_f32_e32 v33, 0x3fcc422a, v33
	v_mul_f32_e32 v33, 0xbfb8aa3b, v33
	v_exp_f32_e32 v33, v33
	s_nop 0
	v_add_f32_e32 v33, 1.0, v33
	v_rcp_f32_e32 v42, v33
	v_mul_f32_e32 v33, 0x3d372713, v31
	v_mul_f32_e32 v33, v31, v33
	v_fma_f32 v33, v31, v33, v31
	v_mul_f32_e32 v33, 0x3fcc422a, v33
	v_mul_f32_e32 v33, 0xbfb8aa3b, v33
	v_exp_f32_e32 v33, v33
	s_nop 0
	v_add_f32_e32 v33, 1.0, v33
	v_rcp_f32_e32 v41, v33
	v_mul_f32_e32 v33, 0x3d372713, v27
	v_mul_f32_e32 v33, v27, v33
	v_fma_f32 v33, v27, v33, v27
	v_mul_f32_e32 v33, 0x3fcc422a, v33
	v_mul_f32_e32 v33, 0xbfb8aa3b, v33
	v_exp_f32_e32 v33, v33
	v_pk_mul_f32 v[30:31], v[30:31], v[40:41]
	v_add_f32_e32 v33, 1.0, v33
	v_rcp_f32_e32 v43, v33
	s_nop 0
	v_pk_mul_f32 v[26:27], v[26:27], v[42:43]

; __device__ __forceinline__ unsigned cvt_pk_bf16(float lo, float hi) { unsigned r; asm volatile("v_cvt_pk_bf16_f32 %0, %1, %2" : "=v"(r) : "v"(lo), "v"(hi)); return r; }
; __device__ __forceinline__ float gelu_t(float x) { const float z = 1.5957691216f * (x + 0.044715f * x * x * x); return x * sigm(z); }
; #define EPI_FOR_ROWS() _Pragma("unroll") for (int ai = 0; ai < 2; ++ai) _Pragma("unroll") for (int m = 0; m < 4; ++m)
; __device__ __forceinline__ float row_rstd(const float* ssq, int row, int fq) {
;     const f32x4 q = *(const f32x4*)(ssq + (size_t)row * 16 + 4 * fq); float s = (q[0] + q[1]) + (q[2] + q[3]);
;     s += __shfl_xor(s, 16); s += __shfl_xor(s, 32); return rsqrtf(s * (1.0f / 1024.0f) + EPS);
; }
;     __device__ __forceinline__ void operator()(const f32x4 (&acc)[2][2][4][2], const Unit& u, int wr, int wc, int fr, int fq) const {
;     ...
;         EPI_FOR_ROWS() {
;             const int row = row0 + ai * 128 + m * 16; const float rs = row_rstd(ssq, row, fq);
; #pragma unroll
;             for (int bj = 0; bj < 2; ++bj) { const int col = col0 + bj * 128; f32x4 v0 = acc[ai][bj][m][0] * rs, v1 = acc[ai][bj][m][1] * rs;
;                 if (u.pn >= 2) {
; #pragma unroll
;                     for (int e = 0; e < 4; ++e) { v0[e] = gelu_t(v0[e]); v1[e] = gelu_t(v1[e]); } }
;                 u32x4 w; w.x = cvt_pk_bf16(v0[0], v0[1]); w.y = cvt_pk_bf16(v0[2], v0[3]); w.z = cvt_pk_bf16(v1[0], v1[1]); w.w = cvt_pk_bf16(v1[2], v1[3]);
;                 *(u32x4*)(proj + (size_t)row * 1536 + col) = w; }
.LBB0_264:
	v_cvt_pk_bf16_f32 v20, v20, v21
	v_cvt_pk_bf16_f32 v21, v22, v23
	v_cvt_pk_bf16_f32 v22, v16, v17
	v_add_u32_e32 v16, 0xb0, v130
	v_ashrrev_i32_e32 v17, 31, v16
	v_cvt_pk_bf16_f32 v23, v18, v19
	v_lshlrev_b64 v[18:19], 6, v[16:17]
	global_store_dwordx4 v[24:25], v[20:23], off offset:256
	v_lshl_add_u64 v[18:19], v[128:129], 0, v[18:19]
	v_mov_b32_e32 v18, v198
	v_mov_b32_e32 v19, v199
	v_mov_b32_e32 v20, v200
	v_mov_b32_e32 v21, v201
	s_and_b64 vcc, exec, s[8:9]
	v_mov_b32_e32 v22, v19
	v_mov_b32_e32 v23, v20
	v_mov_b32_e32 v19, v21
	v_pk_add_f32 v[18:19], v[22:23], v[18:19]
	s_nop 0
	v_add_f32_e32 v17, v18, v19
	ds_bpermute_b32 v18, v131, v17
	s_waitcnt lgkmcnt(0)
	v_add_f32_e32 v17, v17, v18
	ds_bpermute_b32 v18, v147, v17
	s_waitcnt lgkmcnt(0)
	v_add_f32_e32 v17, v17, v18
	v_fmamk_f32 v17, v17, 0x3a800000, v208
	v_mul_f32_e32 v18, 0x4b800000, v17
	v_cmp_gt_f32_e64 s[10:11], s44, v17
	s_nop 1
	v_cndmask_b32_e64 v17, v17, v18, s[10:11]
	v_rsq_f32_e32 v17, v17
	s_nop 0
	v_mul_f32_e32 v18, 0x45800000, v17
	v_cndmask_b32_e64 v18, v17, v18, s[10:11]
	v_pk_mul_f32 v[14:15], v[14:15], v[18:19] op_sel_hi:[1,0]
	v_pk_mul_f32 v[12:13], v[12:13], v[18:19] op_sel_hi:[1,0]
	v_pk_mul_f32 v[10:11], v[10:11], v[18:19] op_sel_hi:[1,0]
	v_pk_mul_f32 v[8:9], v[8:9], v[18:19] op_sel_hi:[1,0]
	s_cbranch_vccnz .LBB0_266
	v_mul_f32_e32 v17, 0x3d372713, v12
	v_mul_f32_e32 v17, v12, v17
	v_fma_f32 v17, v12, v17, v12
	v_mul_f32_e32 v17, 0x3fcc422a, v17
	v_mul_f32_e32 v17, 0xbfb8aa3b, v17
	v_exp_f32_e32 v17, v17
	v_mov_b32_e32 v19, v13
	v_add_f32_e32 v17, 1.0, v17
	v_rcp_f32_e32 v20, v17
	v_mul_f32_e32 v17, 0x3d372713, v8
	v_mul_f32_e32 v17, v8, v17
	v_fma_f32 v17, v8, v17, v8
	v_mul_f32_e32 v17, 0x3fcc422a, v17
	v_mul_f32_e32 v17, 0xbfb8aa3b, v17
	v_exp_f32_e32 v17, v17
	s_nop 0
	v_add_f32_e32 v17, 1.0, v17
	v_rcp_f32_e32 v22, v17
	v_mul_f32_e32 v17, 0x3d372713, v13
	v_mul_f32_e32 v17, v13, v17
	v_fmac_f32_e32 v19, v19, v17
	v_mul_f32_e32 v17, 0x3fcc422a, v19
	v_mul_f32_e32 v17, 0xbfb8aa3b, v17
	v_exp_f32_e32 v17, v17
	v_mov_b32_e32 v19, v9
	v_add_f32_e32 v17, 1.0, v17
	v_rcp_f32_e32 v21, v17
	v_mul_f32_e32 v17, 0x3d372713, v9
	v_mul_f32_e32 v17, v9, v17
	v_fmac_f32_e32 v19, v19, v17
	v_mul_f32_e32 v17, 0x3fcc422a, v19
	v_mul_f32_e32 v17, 0xbfb8aa3b, v17
	v_exp_f32_e32 v17, v17
	v_pk_mul_f32 v[12:13], v[12:13], v[20:21]
	v_add_f32_e32 v17, 1.0, v17
	v_rcp_f32_e32 v23, v17
	v_mul_f32_e32 v17, 0x3d372713, v14
	v_mul_f32_e32 v17, v14, v17
	v_fma_f32 v17, v14, v17, v14
	v_mul_f32_e32 v17, 0x3fcc422a, v17
	v_mul_f32_e32 v17, 0xbfb8aa3b, v17
	v_exp_f32_e32 v17, v17
	v_pk_mul_f32 v[8:9], v[8:9], v[22:23]
	v_add_f32_e32 v17, 1.0, v17
	v_rcp_f32_e32 v24, v17
	v_mul_f32_e32 v17, 0x3d372713, v10
	v_mul_f32_e32 v17, v10, v17
	v_fma_f32 v17, v10, v17, v10
	v_mul_f32_e32 v17, 0x3fcc422a, v17
	v_mul_f32_e32 v17, 0xbfb8aa3b, v17
	v_exp_f32_e32 v17, v17
	s_nop 0
	v_add_f32_e32 v17, 1.0, v17
	v_rcp_f32_e32 v26, v17
	v_mul_f32_e32 v17, 0x3d372713, v15
	v_mul_f32_e32 v17, v15, v17
	v_fma_f32 v17, v15, v17, v15
	v_mul_f32_e32 v17, 0x3fcc422a, v17
	v_mul_f32_e32 v17, 0xbfb8aa3b, v17
	v_exp_f32_e32 v17, v17
	s_nop 0
	v_add_f32_e32 v17, 1.0, v17
	v_rcp_f32_e32 v25, v17
	v_mul_f32_e32 v17, 0x3d372713, v11
	v_mul_f32_e32 v17, v11, v17
	v_fma_f32 v17, v11, v17, v11
	v_mul_f32_e32 v17, 0x3fcc422a, v17
	v_mul_f32_e32 v17, 0xbfb8aa3b, v17
	v_exp_f32_e32 v17, v17
	v_pk_mul_f32 v[14:15], v[14:15], v[24:25]
	v_add_f32_e32 v17, 1.0, v17
	v_rcp_f32_e32 v27, v17
	s_nop 0
	v_pk_mul_f32 v[10:11], v[10:11], v[26:27]

; #define LAS __attribute__((address_space(3)))
; __device__ __forceinline__ unsigned cvt_pk_bf16(float lo, float hi) { unsigned r; asm volatile("v_cvt_pk_bf16_f32 %0, %1, %2" : "=v"(r) : "v"(lo), "v"(hi)); return r; }
; #define EPI_FOR_ROWS() _Pragma("unroll") for (int ai = 0; ai < 2; ++ai) _Pragma("unroll") for (int m = 0; m < 4; ++m)
; __device__ __forceinline__ float row_rstd(const float* ssq, int row, int fq) {
;     const f32x4 q = *(const f32x4*)(ssq + (size_t)row * 16 + 4 * fq); float s = (q[0] + q[1]) + (q[2] + q[3]);
;     s += __shfl_xor(s, 16); s += __shfl_xor(s, 32); return rsqrtf(s * (1.0f / 1024.0f) + EPS);
; }
;     __device__ __forceinline__ void operator()(f32x4 (&acc)[2][2][4][2], const Unit& u, int wr, int wc, int fr, int fq) const {
;     ...
;         EPI_FOR_ROWS() { const int row = row0 + ai * 128 + m * 16; const float rs = row_rstd(ssq, row, fq);
;             acc[ai][0][m][0] = (acc[ai][0][m][0] * rs) * (acc[ai][0][m][1] * rs); acc[ai][1][m][0] *= rs;
;             const f32x4 uu = acc[ai][1][m][1] * rs; u32x2 w; w.x = cvt_pk_bf16(uu[0], uu[1]); w.y = cvt_pk_bf16(uu[2], uu[3]);
;             *(u32x2*)(a2 + ((size_t)(ch >> 4) * 2048 + (row >> 4)) * 384 + (row & 15) * 16 + (ch & 15)) = w; }
;         if (fr >= 14) {
; #pragma unroll
;             for (int ai = 0; ai < 2; ++ai) *(LAS f32x4*)(hl + ((((ai * 2 + wr) * 4 + wc) * 2 + (fr - 14)) * 16 + fq * 4)) = acc[ai][0][3][0];
;             if (wr == 1) *(f32x4*)(tail + ((size_t)u.pm * 2 + (fr - 14)) * 512 + ch) = acc[1][0][3][0]; }
.LBB0_587:
	s_lshl_b32 s8, s12, 8
	v_mov_b32_e32 v134, v148
	s_add_i32 s8, s8, s54
	v_and_b32_e32 v133, 64, v207
	v_mov_b32_e32 v146, v149
	v_add_u32_e32 v132, s8, v134
	s_lshl_b32 s8, s13, 6
	v_xor_b32_e32 v131, 16, v207
	v_add_u32_e32 v133, 64, v133
	s_or_b32 s8, s8, s62
	v_lshlrev_b32_e32 v128, 2, v146
	v_cmp_lt_i32_e32 vcc, v131, v133
	v_xor_b32_e32 v135, 32, v207
	v_add_u32_e32 v130, s8, v128
	v_cndmask_b32_e32 v131, v207, v131, vcc
	v_cmp_lt_i32_e32 vcc, v135, v133
	v_ashrrev_i32_e32 v136, 4, v130
	v_ashrrev_i32_e32 v137, 31, v136
	v_cndmask_b32_e32 v133, v207, v135, vcc
	v_lshlrev_b32_e32 v135, 2, v133
	v_ashrrev_i32_e32 v133, 31, v132
	v_ashrrev_i32_e32 v129, 31, v128
	v_lshlrev_b64 v[138:139], 11, v[136:137]
	v_lshlrev_b64 v[136:137], 6, v[132:133]
	v_lshl_add_u64 v[136:137], s[20:21], 0, v[136:137]
	v_lshlrev_b64 v[140:141], 2, v[128:129]
	v_lshl_add_u64 v[136:137], v[136:137], 0, v[140:141]
	global_load_dwordx4 v[182:185], v[136:137], off
	global_load_dwordx4 v[186:189], v[136:137], off offset:1024
	global_load_dwordx4 v[190:193], v[136:137], off offset:2048
	global_load_dwordx4 v[194:197], v[136:137], off offset:3072
	v_mov_b32_e32 v200, 0x2000
	v_mov_b32_e32 v201, 0
	v_lshl_add_u64 v[198:199], v[136:137], 0, v[200:201]
	global_load_dwordx4 v[198:201], v[198:199], off
	v_mov_b32_e32 v204, 0x2400
	v_mov_b32_e32 v205, 0
	v_lshl_add_u64 v[202:203], v[136:137], 0, v[204:205]
	global_load_dwordx4 v[202:205], v[202:203], off
	v_mov_b32_e32 v216, 0x2800
	v_mov_b32_e32 v217, 0
	v_lshl_add_u64 v[214:215], v[136:137], 0, v[216:217]
	global_load_dwordx4 v[214:217], v[214:215], off
	v_mov_b32_e32 v220, 0x2c00
	v_mov_b32_e32 v221, 0
	v_lshl_add_u64 v[218:219], v[136:137], 0, v[220:221]
	global_load_dwordx4 v[218:221], v[218:219], off
	s_waitcnt vmcnt(0)
	v_mov_b32_e32 v142, v182
	v_mov_b32_e32 v143, v183
	v_mov_b32_e32 v144, v184
	v_mov_b32_e32 v145, v185
	v_lshlrev_b32_e32 v131, 2, v131
	v_readlane_b32 s8, v252, 40
	v_readlane_b32 s9, v252, 41
	v_mov_b32_e32 v136, v143
	v_mov_b32_e32 v137, v144
	v_mov_b32_e32 v143, v145
	v_pk_add_f32 v[136:137], v[136:137], v[142:143]
	v_mov_b64_e32 v[142:143], s[8:9]
	v_add_f32_e32 v129, v136, v137
	ds_bpermute_b32 v136, v131, v129
	s_waitcnt lgkmcnt(0)
	v_add_f32_e32 v129, v129, v136
	ds_bpermute_b32 v136, v135, v129
	s_waitcnt lgkmcnt(0)
	v_add_f32_e32 v129, v129, v136
	v_fmamk_f32 v129, v129, 0x3a800000, v208
	v_cmp_gt_f32_e32 vcc, s44, v129
	v_mul_f32_e32 v136, 0x4b800000, v129
	s_nop 0
	v_cndmask_b32_e32 v129, v129, v136, vcc
	v_rsq_f32_e32 v129, v129
	s_nop 0
	v_mul_f32_e32 v136, 0x45800000, v129
	v_cndmask_b32_e32 v136, v129, v136, vcc
	v_pk_mul_f32 v[126:127], v[126:127], v[136:137] op_sel_hi:[1,0]
	v_pk_mul_f32 v[124:125], v[124:125], v[136:137] op_sel_hi:[1,0]
	v_lshlrev_b32_e32 v129, 3, v146
	v_cvt_pk_bf16_f32 v124, v124, v125
	v_cvt_pk_bf16_f32 v125, v126, v127
	v_ashrrev_i32_e32 v126, 4, v132
	v_ashrrev_i32_e32 v127, 31, v126
	v_lshl_add_u64 v[126:127], v[138:139], 0, v[126:127]
	v_mad_u64_u32 v[144:145], s[8:9], v126, s41, v[142:143]
	v_lshlrev_b32_e32 v126, 5, v134
	v_mad_i32_i24 v145, v127, s41, v145
	v_and_b32_e32 v160, 0x1e0, v126
	v_lshl_add_u64 v[126:127], v[144:145], 0, v[160:161]
	v_and_b32_e32 v144, 24, v129
	v_mov_b32_e32 v145, v161
	v_lshl_add_u64 v[126:127], v[126:127], 0, v[144:145]
	global_store_dwordx2 v[126:127], v[124:125], off
	v_add_u32_e32 v124, 16, v132
	v_ashrrev_i32_e32 v125, 31, v124
	v_lshlrev_b64 v[126:127], 6, v[124:125]
	v_lshl_add_u64 v[126:127], s[20:21], 0, v[126:127]
	v_lshl_add_u64 v[126:127], v[126:127], 0, v[140:141]
	v_mov_b32_e32 v178, v186
	v_mov_b32_e32 v179, v187
	v_mov_b32_e32 v180, v188
	v_mov_b32_e32 v181, v189
	v_mov_b32_e32 v126, v179
	v_mov_b32_e32 v127, v180
	v_mov_b32_e32 v179, v181
	v_pk_add_f32 v[126:127], v[126:127], v[178:179]
	s_nop 0
	v_add_f32_e32 v126, v126, v127
	ds_bpermute_b32 v127, v131, v126
	s_waitcnt lgkmcnt(0)
	v_add_f32_e32 v126, v126, v127
	ds_bpermute_b32 v127, v135, v126
	s_waitcnt lgkmcnt(0)
	v_add_f32_e32 v126, v126, v127
	v_fmamk_f32 v126, v126, 0x3a800000, v208
	v_cmp_gt_f32_e32 vcc, s44, v126
	v_mul_f32_e32 v127, 0x4b800000, v126
	s_nop 0
	v_cndmask_b32_e32 v126, v126, v127, vcc
	v_rsq_f32_e32 v126, v126
	s_nop 0
	v_mul_f32_e32 v127, 0x45800000, v126
	v_cndmask_b32_e32 v126, v126, v127, vcc
	v_pk_mul_f32 v[122:123], v[122:123], v[126:127] op_sel_hi:[1,0]
	v_pk_mul_f32 v[120:121], v[120:121], v[126:127] op_sel_hi:[1,0]
	s_nop 0
	v_cvt_pk_bf16_f32 v120, v120, v121
	v_cvt_pk_bf16_f32 v121, v122, v123
	v_ashrrev_i32_e32 v122, 4, v124
	v_ashrrev_i32_e32 v123, 31, v122
	v_lshl_add_u64 v[122:123], v[138:139], 0, v[122:123]
	v_mad_u64_u32 v[146:147], s[8:9], v122, s41, v[142:143]
	v_mad_i32_i24 v147, v123, s41, v147
	v_lshl_add_u64 v[122:123], v[146:147], 0, v[160:161]
	v_lshl_add_u64 v[122:123], v[122:123], 0, v[144:145]
	global_store_dwordx2 v[122:123], v[120:121], off
	v_add_u32_e32 v120, 32, v132
	v_ashrrev_i32_e32 v121, 31, v120
	v_lshlrev_b64 v[122:123], 6, v[120:121]
	v_lshl_add_u64 v[122:123], s[20:21], 0, v[122:123]
	v_lshl_add_u64 v[122:123], v[122:123], 0, v[140:141]
	v_mov_b32_e32 v178, v190
	v_mov_b32_e32 v179, v191
	v_mov_b32_e32 v180, v192
	v_mov_b32_e32 v181, v193
	v_mov_b32_e32 v122, v179
	v_mov_b32_e32 v123, v180
	v_mov_b32_e32 v179, v181
	v_pk_add_f32 v[122:123], v[122:123], v[178:179]
	s_nop 0
	v_add_f32_e32 v122, v122, v123
	ds_bpermute_b32 v123, v131, v122
	s_waitcnt lgkmcnt(0)
	v_add_f32_e32 v122, v122, v123
	ds_bpermute_b32 v123, v135, v122
	s_waitcnt lgkmcnt(0)
; #define LAS __attribute__((address_space(3)))
; __device__ __forceinline__ unsigned cvt_pk_bf16(float lo, float hi) { unsigned r; asm volatile("v_cvt_pk_bf16_f32 %0, %1, %2" : "=v"(r) : "v"(lo), "v"(hi)); return r; }
; #define EPI_FOR_ROWS() _Pragma("unroll") for (int ai = 0; ai < 2; ++ai) _Pragma("unroll") for (int m = 0; m < 4; ++m)
; __device__ __forceinline__ float row_rstd(const float* ssq, int row, int fq) {
;     const f32x4 q = *(const f32x4*)(ssq + (size_t)row * 16 + 4 * fq); float s = (q[0] + q[1]) + (q[2] + q[3]);
;     s += __shfl_xor(s, 16); s += __shfl_xor(s, 32); return rsqrtf(s * (1.0f / 1024.0f) + EPS);
; }
;     __device__ __forceinline__ void operator()(f32x4 (&acc)[2][2][4][2], const Unit& u, int wr, int wc, int fr, int fq) const {
;     ...
;         EPI_FOR_ROWS() { const int row = row0 + ai * 128 + m * 16; const float rs = row_rstd(ssq, row, fq);
;             acc[ai][0][m][0] = (acc[ai][0][m][0] * rs) * (acc[ai][0][m][1] * rs); acc[ai][1][m][0] *= rs;
;             const f32x4 uu = acc[ai][1][m][1] * rs; u32x2 w; w.x = cvt_pk_bf16(uu[0], uu[1]); w.y = cvt_pk_bf16(uu[2], uu[3]);
;             *(u32x2*)(a2 + ((size_t)(ch >> 4) * 2048 + (row >> 4)) * 384 + (row & 15) * 16 + (ch & 15)) = w; }
;         if (fr >= 14) {
; #pragma unroll
;             for (int ai = 0; ai < 2; ++ai) *(LAS f32x4*)(hl + ((((ai * 2 + wr) * 4 + wc) * 2 + (fr - 14)) * 16 + fq * 4)) = acc[ai][0][3][0];
;             if (wr == 1) *(f32x4*)(tail + ((size_t)u.pm * 2 + (fr - 14)) * 512 + ch) = acc[1][0][3][0]; }
	v_add_f32_e32 v122, v122, v123
	v_fmamk_f32 v122, v122, 0x3a800000, v208
	v_cmp_gt_f32_e32 vcc, s44, v122
	v_mul_f32_e32 v123, 0x4b800000, v122
	s_nop 0
	v_cndmask_b32_e32 v122, v122, v123, vcc
	v_rsq_f32_e32 v122, v122
	s_nop 0
	v_mul_f32_e32 v123, 0x45800000, v122
	v_cndmask_b32_e32 v122, v122, v123, vcc
	v_pk_mul_f32 v[118:119], v[118:119], v[122:123] op_sel_hi:[1,0]
	v_pk_mul_f32 v[116:117], v[116:117], v[122:123] op_sel_hi:[1,0]
	s_nop 0
	v_cvt_pk_bf16_f32 v116, v116, v117
	v_cvt_pk_bf16_f32 v117, v118, v119
	v_ashrrev_i32_e32 v118, 4, v120
	v_ashrrev_i32_e32 v119, 31, v118
	v_lshl_add_u64 v[118:119], v[138:139], 0, v[118:119]
	v_mad_u64_u32 v[146:147], s[8:9], v118, s41, v[142:143]
	v_mad_i32_i24 v147, v119, s41, v147
	v_lshl_add_u64 v[118:119], v[146:147], 0, v[160:161]
	v_lshl_add_u64 v[118:119], v[118:119], 0, v[144:145]
	global_store_dwordx2 v[118:119], v[116:117], off
	v_add_u32_e32 v116, 48, v132
	v_ashrrev_i32_e32 v117, 31, v116
	v_lshlrev_b64 v[118:119], 6, v[116:117]
	v_lshl_add_u64 v[118:119], s[20:21], 0, v[118:119]
	v_lshl_add_u64 v[118:119], v[118:119], 0, v[140:141]
	v_mov_b32_e32 v178, v194
	v_mov_b32_e32 v179, v195
	v_mov_b32_e32 v180, v196
	v_mov_b32_e32 v181, v197
	v_mov_b32_e32 v118, v179
	v_mov_b32_e32 v119, v180
	v_mov_b32_e32 v179, v181
	v_pk_add_f32 v[118:119], v[118:119], v[178:179]
	s_nop 0
	v_add_f32_e32 v118, v118, v119
	ds_bpermute_b32 v119, v131, v118
	s_waitcnt lgkmcnt(0)
	v_add_f32_e32 v118, v118, v119
	ds_bpermute_b32 v119, v135, v118
	s_waitcnt lgkmcnt(0)
	v_add_f32_e32 v118, v118, v119
	v_fmamk_f32 v118, v118, 0x3a800000, v208
	v_cmp_gt_f32_e32 vcc, s44, v118
	v_mul_f32_e32 v119, 0x4b800000, v118
	s_nop 0
	v_cndmask_b32_e32 v118, v118, v119, vcc
	v_rsq_f32_e32 v118, v118
	s_nop 0
	v_mul_f32_e32 v119, 0x45800000, v118
	v_cndmask_b32_e32 v118, v118, v119, vcc
	v_pk_mul_f32 v[110:111], v[110:111], v[118:119] op_sel_hi:[1,0]
	v_pk_mul_f32 v[108:109], v[108:109], v[118:119] op_sel_hi:[1,0]
	v_pk_mul_f32 v[112:113], v[112:113], v[118:119] op_sel_hi:[1,0]
	v_cvt_pk_bf16_f32 v108, v108, v109
	v_cvt_pk_bf16_f32 v109, v110, v111
	v_ashrrev_i32_e32 v110, 4, v116
	v_ashrrev_i32_e32 v111, 31, v110
	v_pk_mul_f32 v[104:105], v[104:105], v[118:119] op_sel_hi:[1,0]
	v_lshl_add_u64 v[110:111], v[138:139], 0, v[110:111]
	v_pk_mul_f32 v[104:105], v[112:113], v[104:105]
	v_mad_u64_u32 v[112:113], s[8:9], v110, s41, v[142:143]
	v_mad_i32_i24 v113, v111, s41, v113
	v_lshl_add_u64 v[110:111], v[112:113], 0, v[160:161]
	v_lshl_add_u64 v[110:111], v[110:111], 0, v[144:145]
	global_store_dwordx2 v[110:111], v[108:109], off
	v_add_u32_e32 v108, 0x80, v132
	v_ashrrev_i32_e32 v109, 31, v108
	v_lshlrev_b64 v[110:111], 6, v[108:109]
	v_lshl_add_u64 v[110:111], s[20:21], 0, v[110:111]
	v_lshl_add_u64 v[110:111], v[110:111], 0, v[140:141]
	v_mov_b32_e32 v110, v198
	v_mov_b32_e32 v111, v199
	v_mov_b32_e32 v112, v200
	v_mov_b32_e32 v113, v201
	v_pk_mul_f32 v[114:115], v[114:115], v[118:119] op_sel_hi:[1,0]
	v_pk_mul_f32 v[106:107], v[106:107], v[118:119] op_sel_hi:[1,0]
	s_nop 0
	v_pk_mul_f32 v[106:107], v[114:115], v[106:107]
	v_mov_b32_e32 v114, v111
	v_mov_b32_e32 v115, v112
	v_mov_b32_e32 v111, v113
	v_pk_add_f32 v[110:111], v[114:115], v[110:111]
	s_nop 0
	v_add_f32_e32 v110, v110, v111
	ds_bpermute_b32 v111, v131, v110
	s_waitcnt lgkmcnt(0)
	v_add_f32_e32 v110, v110, v111
	ds_bpermute_b32 v111, v135, v110
	s_waitcnt lgkmcnt(0)
	v_add_f32_e32 v110, v110, v111
	v_fmamk_f32 v110, v110, 0x3a800000, v208
	v_cmp_gt_f32_e32 vcc, s44, v110
	v_mul_f32_e32 v111, 0x4b800000, v110
	s_nop 0
	v_cndmask_b32_e32 v110, v110, v111, vcc
	v_rsq_f32_e32 v110, v110
	s_nop 0
	v_mul_f32_e32 v111, 0x45800000, v110
	v_cndmask_b32_e32 v110, v110, v111, vcc
	v_pk_mul_f32 v[102:103], v[102:103], v[110:111] op_sel_hi:[1,0]
	v_pk_mul_f32 v[100:101], v[100:101], v[110:111] op_sel_hi:[1,0]
	s_nop 0
	v_cvt_pk_bf16_f32 v100, v100, v101
	v_cvt_pk_bf16_f32 v101, v102, v103
	v_ashrrev_i32_e32 v102, 4, v108
	v_ashrrev_i32_e32 v103, 31, v102
	v_lshl_add_u64 v[102:103], v[138:139], 0, v[102:103]
	v_mad_u64_u32 v[112:113], s[8:9], v102, s41, v[142:143]
	v_mad_i32_i24 v113, v103, s41, v113
	v_lshl_add_u64 v[102:103], v[112:113], 0, v[160:161]
	v_lshl_add_u64 v[102:103], v[102:103], 0, v[144:145]
	global_store_dwordx2 v[102:103], v[100:101], off
	v_add_u32_e32 v100, 0x90, v132
	v_ashrrev_i32_e32 v101, 31, v100
	v_lshlrev_b64 v[102:103], 6, v[100:101]
	v_lshl_add_u64 v[102:103], s[20:21], 0, v[102:103]
	v_lshl_add_u64 v[102:103], v[102:103], 0, v[140:141]
	v_mov_b32_e32 v112, v202
	v_mov_b32_e32 v113, v203
	v_mov_b32_e32 v114, v204
	v_mov_b32_e32 v115, v205
	v_mov_b32_e32 v102, v113
	v_mov_b32_e32 v103, v114
	v_mov_b32_e32 v113, v115
	v_pk_add_f32 v[102:103], v[102:103], v[112:113]
	s_nop 0
	v_add_f32_e32 v102, v102, v103
	ds_bpermute_b32 v103, v131, v102
	s_waitcnt lgkmcnt(0)
	v_add_f32_e32 v102, v102, v103
	ds_bpermute_b32 v103, v135, v102
	s_waitcnt lgkmcnt(0)
; #define LAS __attribute__((address_space(3)))
; __device__ __forceinline__ unsigned cvt_pk_bf16(float lo, float hi) { unsigned r; asm volatile("v_cvt_pk_bf16_f32 %0, %1, %2" : "=v"(r) : "v"(lo), "v"(hi)); return r; }
; #define EPI_FOR_ROWS() _Pragma("unroll") for (int ai = 0; ai < 2; ++ai) _Pragma("unroll") for (int m = 0; m < 4; ++m)
; __device__ __forceinline__ float row_rstd(const float* ssq, int row, int fq) {
;     const f32x4 q = *(const f32x4*)(ssq + (size_t)row * 16 + 4 * fq); float s = (q[0] + q[1]) + (q[2] + q[3]);
;     s += __shfl_xor(s, 16); s += __shfl_xor(s, 32); return rsqrtf(s * (1.0f / 1024.0f) + EPS);
; }
;     __device__ __forceinline__ void operator()(f32x4 (&acc)[2][2][4][2], const Unit& u, int wr, int wc, int fr, int fq) const {
;     ...
;         EPI_FOR_ROWS() { const int row = row0 + ai * 128 + m * 16; const float rs = row_rstd(ssq, row, fq);
;             acc[ai][0][m][0] = (acc[ai][0][m][0] * rs) * (acc[ai][0][m][1] * rs); acc[ai][1][m][0] *= rs;
;             const f32x4 uu = acc[ai][1][m][1] * rs; u32x2 w; w.x = cvt_pk_bf16(uu[0], uu[1]); w.y = cvt_pk_bf16(uu[2], uu[3]);
;             *(u32x2*)(a2 + ((size_t)(ch >> 4) * 2048 + (row >> 4)) * 384 + (row & 15) * 16 + (ch & 15)) = w; }
;         if (fr >= 14) {
; #pragma unroll
;             for (int ai = 0; ai < 2; ++ai) *(LAS f32x4*)(hl + ((((ai * 2 + wr) * 4 + wc) * 2 + (fr - 14)) * 16 + fq * 4)) = acc[ai][0][3][0];
;             if (wr == 1) *(f32x4*)(tail + ((size_t)u.pm * 2 + (fr - 14)) * 512 + ch) = acc[1][0][3][0]; }
	v_add_f32_e32 v102, v102, v103
	v_fmamk_f32 v102, v102, 0x3a800000, v208
	v_cmp_gt_f32_e32 vcc, s44, v102
	v_mul_f32_e32 v103, 0x4b800000, v102
	s_nop 0
	v_cndmask_b32_e32 v102, v102, v103, vcc
	v_rsq_f32_e32 v102, v102
	s_nop 0
	v_mul_f32_e32 v103, 0x45800000, v102
	v_cndmask_b32_e32 v112, v102, v103, vcc
	v_pk_mul_f32 v[98:99], v[98:99], v[112:113] op_sel_hi:[1,0]
	v_pk_mul_f32 v[96:97], v[96:97], v[112:113] op_sel_hi:[1,0]
	s_nop 0
	v_cvt_pk_bf16_f32 v96, v96, v97
	v_cvt_pk_bf16_f32 v97, v98, v99
	v_ashrrev_i32_e32 v98, 4, v100
	v_ashrrev_i32_e32 v99, 31, v98
	v_lshl_add_u64 v[98:99], v[138:139], 0, v[98:99]
	v_mad_u64_u32 v[102:103], s[8:9], v98, s41, v[142:143]
	v_mad_i32_i24 v103, v99, s41, v103
	v_lshl_add_u64 v[98:99], v[102:103], 0, v[160:161]
	v_add_u32_e32 v102, 0xa0, v132
	v_lshl_add_u64 v[98:99], v[98:99], 0, v[144:145]
	v_ashrrev_i32_e32 v103, 31, v102
	global_store_dwordx2 v[98:99], v[96:97], off
	v_lshlrev_b64 v[96:97], 6, v[102:103]
	v_lshl_add_u64 v[96:97], s[20:21], 0, v[96:97]
	v_lshl_add_u64 v[96:97], v[96:97], 0, v[140:141]
	v_mov_b32_e32 v96, v214
	v_mov_b32_e32 v97, v215
	v_mov_b32_e32 v98, v216
	v_mov_b32_e32 v99, v217
	v_mov_b32_e32 v114, v97
	v_mov_b32_e32 v115, v98
	v_mov_b32_e32 v97, v99
	v_pk_add_f32 v[96:97], v[114:115], v[96:97]
	v_add_u32_e32 v114, 0xb0, v132
	v_add_f32_e32 v96, v96, v97
	ds_bpermute_b32 v97, v131, v96
	v_ashrrev_i32_e32 v115, 31, v114
	s_waitcnt lgkmcnt(0)
	v_add_f32_e32 v96, v96, v97
	ds_bpermute_b32 v97, v135, v96
	s_waitcnt lgkmcnt(0)
	v_add_f32_e32 v96, v96, v97
	v_fmamk_f32 v96, v96, 0x3a800000, v208
	v_cmp_gt_f32_e32 vcc, s44, v96
	v_mul_f32_e32 v97, 0x4b800000, v96
	s_nop 0
	v_cndmask_b32_e32 v96, v96, v97, vcc
	v_rsq_f32_e32 v96, v96
	s_nop 0
	v_mul_f32_e32 v97, 0x45800000, v96
	v_cndmask_b32_e32 v146, v96, v97, vcc
	v_pk_mul_f32 v[94:95], v[94:95], v[146:147] op_sel_hi:[1,0]
	v_pk_mul_f32 v[92:93], v[92:93], v[146:147] op_sel_hi:[1,0]
	s_nop 0
	v_cvt_pk_bf16_f32 v92, v92, v93
	v_cvt_pk_bf16_f32 v93, v94, v95
	v_ashrrev_i32_e32 v94, 4, v102
	v_ashrrev_i32_e32 v95, 31, v94
	v_lshl_add_u64 v[94:95], v[138:139], 0, v[94:95]
	v_mad_u64_u32 v[96:97], s[8:9], v94, s41, v[142:143]
	v_mad_i32_i24 v97, v95, s41, v97
	v_lshl_add_u64 v[94:95], v[96:97], 0, v[160:161]
	v_lshl_add_u64 v[94:95], v[94:95], 0, v[144:145]
	global_store_dwordx2 v[94:95], v[92:93], off
	v_lshlrev_b64 v[92:93], 6, v[114:115]
	v_lshl_add_u64 v[92:93], s[20:21], 0, v[92:93]
	v_lshl_add_u64 v[92:93], v[92:93], 0, v[140:141]
	v_mov_b32_e32 v92, v218
	v_mov_b32_e32 v93, v219
	v_mov_b32_e32 v94, v220
	v_mov_b32_e32 v95, v221
	v_mov_b32_e32 v96, v93
	v_mov_b32_e32 v97, v94
	v_mov_b32_e32 v93, v95
	v_pk_add_f32 v[92:93], v[96:97], v[92:93]
	s_nop 0
	v_add_f32_e32 v92, v92, v93
	ds_bpermute_b32 v93, v131, v92
	s_waitcnt lgkmcnt(0)
	v_add_f32_e32 v92, v92, v93
	ds_bpermute_b32 v93, v135, v92
	s_waitcnt lgkmcnt(0)
	v_add_f32_e32 v92, v92, v93
	v_fmamk_f32 v92, v92, 0x3a800000, v208
	v_cmp_gt_f32_e32 vcc, s44, v92
	v_mul_f32_e32 v93, 0x4b800000, v92
	s_nop 0
	v_cndmask_b32_e32 v92, v92, v93, vcc
	v_rsq_f32_e32 v92, v92
	s_nop 0
	v_mul_f32_e32 v93, 0x45800000, v92
	v_cndmask_b32_e32 v140, v92, v93, vcc
	v_pk_mul_f32 v[82:83], v[82:83], v[140:141] op_sel_hi:[1,0]
	v_pk_mul_f32 v[80:81], v[80:81], v[140:141] op_sel_hi:[1,0]
	v_pk_mul_f32 v[88:89], v[88:89], v[140:141] op_sel_hi:[1,0]
	v_cvt_pk_bf16_f32 v80, v80, v81
	v_cvt_pk_bf16_f32 v81, v82, v83
	v_ashrrev_i32_e32 v82, 4, v114
	v_ashrrev_i32_e32 v83, 31, v82
	v_pk_mul_f32 v[84:85], v[84:85], v[140:141] op_sel_hi:[1,0]
	v_lshl_add_u64 v[82:83], v[138:139], 0, v[82:83]
	v_pk_mul_f32 v[84:85], v[88:89], v[84:85]
	v_mad_u64_u32 v[88:89], s[8:9], v82, s41, v[142:143]
	v_mad_i32_i24 v89, v83, s41, v89
	v_lshl_add_u64 v[82:83], v[88:89], 0, v[160:161]
	v_lshl_add_u64 v[82:83], v[82:83], 0, v[144:145]
	v_pk_mul_f32 v[90:91], v[90:91], v[140:141] op_sel_hi:[1,0]
	v_pk_mul_f32 v[86:87], v[86:87], v[140:141] op_sel_hi:[1,0]
	global_store_dwordx2 v[82:83], v[80:81], off
	v_cndmask_b32_e64 v80, 0, 1, s[0:1]
	v_pk_mul_f32 v[86:87], v[90:91], v[86:87]
	v_cmp_lt_i32_e32 vcc, 13, v134
	v_cmp_ne_u32_e64 s[8:9], 1, v80
	s_and_saveexec_b64 s[10:11], vcc
	s_cbranch_execz .LBB0_590
	v_lshlrev_b32_e32 v80, 6, v134
	v_lshlrev_b32_e32 v81, 2, v128
	v_add3_u32 v80, s65, v80, v81
	v_add_u32_e32 v81, 0xfffffc80, v80
	s_and_b64 vcc, exec, s[8:9]
	ds_write_b128 v81, v[104:107]
	ds_write_b128 v80, v[84:87] offset:128
	s_cbranch_vccnz .LBB0_590
	s_ashr_i32 s13, s12, 31
	s_lshl_b64 s[68:69], s[12:13], 12
	v_readlane_b32 s84, v252, 23
	v_add_u32_e32 v160, -14, v134
	v_readlane_b32 s85, v252, 24
	s_add_u32 s68, s84, s68
	s_addc_u32 s69, s85, s69
	v_lshlrev_b64 v[80:81], 11, v[160:161]
	v_lshl_add_u64 v[80:81], s[68:69], 0, v[80:81]
	v_ashrrev_i32_e32 v131, 31, v130
	v_lshl_add_u64 v[80:81], v[130:131], 2, v[80:81]
	global_store_dwordx4 v[80:81], v[84:87], off
